# grid barrier: non-leader workgroups poll the top generation word directly (skip per-XCD relay hop) + relaxed waits + sc1 gemm1 stores
# baseline (speedup 1.0000x reference)
; __device__ __forceinline__ unsigned xb_ld(unsigned* p)              { return __hip_atomic_load(p, __ATOMIC_RELAXED, __HIP_MEMORY_SCOPE_AGENT); }
; __device__ __forceinline__ unsigned xb_add(unsigned* p, unsigned v) { return __hip_atomic_fetch_add(p, v, __ATOMIC_RELAXED, __HIP_MEMORY_SCOPE_AGENT); }
; #define XB_SPIN(cond, bar) do { unsigned _sp = 0; while (cond) { __builtin_amdgcn_s_sleep(1); \
;     if ((++_sp & 255u) == 0u) { if (xb_ld(&(bar)[XB_TMO])) break; if (_sp > XB_SPIN_CAP) { atomicAdd(&(bar)[XB_TMO], 1u); break; } } } } while (0)
; __device__ __forceinline__ void xcd_barrier(const XcdBarrier& b) {
;     ...
;         const unsigned old = xb_add(&bar[XB_XSUB(b.x)], 1u);
;         const unsigned gen = old / nloc;
;         if (old + 1u == (gen + 1u) * nloc) {
;             __builtin_amdgcn_fence(__ATOMIC_RELEASE, "agent");
;             asm volatile("s_waitcnt vmcnt(0)" ::: "memory");
;             const unsigned og = xb_add(&bar[XB_TOP], 1u);
;             const unsigned tg = og / nx;
;             if (og + 1u == (tg + 1u) * nx) xb_add(&bar[XB_TOPGEN], 1u);
;             else XB_SPIN(xb_ld(&bar[XB_TOPGEN]) == tg, bar);
;             __builtin_amdgcn_fence(__ATOMIC_ACQUIRE, "agent");
;             xb_add(&bar[XB_XGEN(b.x)], 1u);
;             asm volatile("s_waitcnt vmcnt(0)" ::: "memory");
;         } else {
;             XB_SPIN(xb_ld(&bar[XB_XGEN(b.x)]) == gen, bar);
.LBB0_777:
	s_or_b64 exec, exec, s[30:31]
	v_cvt_f32_u32_e32 v6, v4
	s_waitcnt vmcnt(0)
	v_readfirstlane_b32 s2, v5
	v_sub_u32_e32 v5, 0, v4
	v_rcp_iflag_f32_e32 v6, v6
	v_add_u32_e32 v7, s2, v3
	v_mul_f32_e32 v6, 0x4f7ffffe, v6
	v_cvt_u32_f32_e32 v6, v6
	v_mul_lo_u32 v3, v5, v6
	v_mul_hi_u32 v3, v6, v3
	v_add_u32_e32 v3, v6, v3
	v_mul_hi_u32 v3, v7, v3
	v_mul_lo_u32 v5, v3, v4
	v_sub_u32_e32 v5, v7, v5
	v_add_u32_e32 v6, 1, v3
	v_cmp_ge_u32_e32 vcc, v5, v4
	s_nop 1
	v_cndmask_b32_e32 v3, v3, v6, vcc
	v_sub_u32_e32 v6, v5, v4
	v_cndmask_b32_e32 v5, v5, v6, vcc
	v_add_u32_e32 v6, 1, v3
	v_cmp_ge_u32_e32 vcc, v5, v4
	v_add_u32_e32 v5, 1, v7
	s_nop 0
	v_cndmask_b32_e32 v3, v3, v6, vcc
	v_mul_lo_u32 v6, v4, v3
	v_add_u32_e32 v4, v6, v4
	v_cmp_ne_u32_e32 vcc, v5, v4
	s_and_saveexec_b64 s[4:5], vcc
	s_xor_b64 s[30:31], exec, s[4:5]
	s_cbranch_execz .LBB0_791
	v_readlane_b32 s4, v253, 51
	v_readlane_b32 s5, v253, 52
	s_waitcnt lgkmcnt(0)
	s_nop 3
	global_load_dword v2, v195, s[4:5] sc1
	s_waitcnt vmcnt(0)
	v_cmp_eq_u32_e32 vcc, v2, v3
	s_and_saveexec_b64 s[36:37], vcc
	s_cbranch_execz .LBB0_790
	s_mov_b32 s2, 1
	s_mov_b64 s[38:39], 0
	s_branch .LBB0_781

; __device__ __forceinline__ unsigned xb_ld(unsigned* p)              { return __hip_atomic_load(p, __ATOMIC_RELAXED, __HIP_MEMORY_SCOPE_AGENT); }
; #define XB_SPIN(cond, bar) do { unsigned _sp = 0; while (cond) { __builtin_amdgcn_s_sleep(1); \
;     if ((++_sp & 255u) == 0u) { if (xb_ld(&(bar)[XB_TMO])) break; if (_sp > XB_SPIN_CAP) { atomicAdd(&(bar)[XB_TMO], 1u); break; } } } } while (0)
; __device__ __forceinline__ void xcd_barrier(const XcdBarrier& b) {
;     ...
;             XB_SPIN(xb_ld(&bar[XB_XGEN(b.x)]) == gen, bar);
.LBB0_785:
	v_readlane_b32 s4, v253, 51
	v_readlane_b32 s5, v253, 52
	s_add_i32 s2, s2, 1
	s_mov_b64 s[44:45], -1
	s_nop 2
	global_load_dword v2, v195, s[4:5] sc1
	s_waitcnt vmcnt(0)
	v_cmp_ne_u32_e32 vcc, v2, v3
	s_orn2_b64 s[42:43], vcc, exec
	s_branch .LBB0_780
